# final_norm: four rows per iteration with all their loads in flight together
# baseline (speedup 1.0000x reference)
.LBB0_3402:
	s_cmp_lt_i32 s42, 25
	s_cselect_b64 s[0:1], -1, 0
	s_cmp_gt_i32 s43, 24
	s_cselect_b64 s[2:3], -1, 0
	s_and_b64 s[0:1], s[0:1], s[2:3]
	s_andn2_b64 vcc, exec, s[0:1]
	s_cbranch_vccnz .LBB0_3460
	v_mbcnt_hi_u32_b32 v0, -1, v210
	v_add_u32_e32 v0, s91, v0
	s_waitcnt lgkmcnt(0)
	s_load_dword s10, s[88:89], 0x160
	s_add_u32 s4, s88, 0x160
	v_readfirstlane_b32 s1, v0
	s_addc_u32 s5, s89, 0
	s_ashr_i32 s1, s1, 6
	s_waitcnt lgkmcnt(0)
	s_mov_b32 s0, s10
	s_lshl_b32 s2, s90, 3
	s_add_i32 s11, s1, s2
	s_cmpk_gt_i32 s11, 0x3fff
	s_cbranch_scc1 .LBB0_3406
	s_load_dwordx4 s[12:15], s[88:89], 0x140
	s_load_dwordx2 s[6:7], s[88:89], 0x150
	s_lshl_b32 s0, s0, 3
	s_ashr_i32 s3, s1, 31
	s_ashr_i32 s9, s2, 31
	s_add_u32 s8, s1, s2
	s_addc_u32 s9, s3, s9
	s_lshl_b64 s[2:3], s[8:9], 6
	s_waitcnt lgkmcnt(0)
	s_add_u32 s1, s6, s2
	s_addc_u32 s3, s7, s3
	s_add_u32 s2, s1, 0x100000
	s_addc_u32 s3, s3, 0
	s_ashr_i32 s1, s0, 31
	s_lshl_b64 s[6:7], s[0:1], 6
	s_lshl_b64 s[8:9], s[8:9], 12
	v_and_b32_e32 v0, 63, v0
	s_add_u32 s8, s14, s8
	v_lshlrev_b32_e32 v0, 4, v0
	v_mov_b32_e32 v1, 0
	s_addc_u32 s9, s15, s9
	v_lshl_add_u64 v[4:5], s[8:9], 0, v[0:1]
	s_mov_b64 s[8:9], 0x800
	v_lshl_add_u64 v[2:3], s[12:13], 0, v[0:1]
	v_lshl_add_u64 v[4:5], v[4:5], 0, s[8:9]
	s_lshl_b64 s[8:9], s[0:1], 12
	v_mov_b32_e32 v0, 0x358637bd
	s_mov_b32 s1, 0x800000
	global_load_dwordx4 v[48:51], v[2:3], off
	global_load_dwordx4 v[52:55], v[2:3], off offset:1024
	global_load_dwordx4 v[56:59], v[2:3], off offset:2048
	global_load_dwordx4 v[60:63], v[2:3], off offset:3072
	s_lshl_b32 s16, s0, 2
	s_lshl_b64 s[18:19], s[6:7], 2
	s_lshl_b64 s[20:21], s[8:9], 2
.LBB0_3405:
	s_mov_b64 s[12:13], s[2:3]
	global_load_dwordx4 v[80:83], v1, s[12:13]
	global_load_dwordx4 v[84:87], v1, s[12:13] offset:16
	global_load_dwordx4 v[88:91], v1, s[12:13] offset:32
	global_load_dwordx4 v[92:95], v1, s[12:13] offset:48
	s_add_u32 s12, s12, s6
	s_addc_u32 s13, s13, s7
	global_load_dwordx4 v[96:99], v1, s[12:13]
	global_load_dwordx4 v[100:103], v1, s[12:13] offset:16
	global_load_dwordx4 v[104:107], v1, s[12:13] offset:32
	global_load_dwordx4 v[108:111], v1, s[12:13] offset:48
	s_add_u32 s12, s12, s6
	s_addc_u32 s13, s13, s7
	global_load_dwordx4 v[112:115], v1, s[12:13]
	global_load_dwordx4 v[116:119], v1, s[12:13] offset:16
	global_load_dwordx4 v[120:123], v1, s[12:13] offset:32
	global_load_dwordx4 v[124:127], v1, s[12:13] offset:48
	s_add_u32 s12, s12, s6
	s_addc_u32 s13, s13, s7
	global_load_dwordx4 v[128:131], v1, s[12:13]
	global_load_dwordx4 v[132:135], v1, s[12:13] offset:16
	global_load_dwordx4 v[136:139], v1, s[12:13] offset:32
	global_load_dwordx4 v[140:143], v1, s[12:13] offset:48
	v_mov_b32_e32 v38, v4
	v_mov_b32_e32 v39, v5
	global_load_dwordx4 v[144:147], v[38:39], off offset:-2048
	global_load_dwordx4 v[148:151], v[38:39], off offset:-1024
	global_load_dwordx4 v[152:155], v[38:39], off
	global_load_dwordx4 v[156:159], v[38:39], off offset:1024
	v_lshl_add_u64 v[38:39], v[38:39], 0, s[8:9]
	global_load_dwordx4 v[160:163], v[38:39], off offset:-2048
	global_load_dwordx4 v[164:167], v[38:39], off offset:-1024
	global_load_dwordx4 v[168:171], v[38:39], off
	global_load_dwordx4 v[172:175], v[38:39], off offset:1024
	v_lshl_add_u64 v[38:39], v[38:39], 0, s[8:9]
	global_load_dwordx4 v[176:179], v[38:39], off offset:-2048
	global_load_dwordx4 v[180:183], v[38:39], off offset:-1024
	global_load_dwordx4 v[184:187], v[38:39], off
	global_load_dwordx4 v[188:191], v[38:39], off offset:1024
	v_lshl_add_u64 v[38:39], v[38:39], 0, s[8:9]
	global_load_dwordx4 v[192:195], v[38:39], off offset:-2048
	global_load_dwordx4 v[196:199], v[38:39], off offset:-1024
	global_load_dwordx4 v[200:203], v[38:39], off
	global_load_dwordx4 v[204:207], v[38:39], off offset:1024
	v_mov_b32_e32 v38, v4
	v_mov_b32_e32 v39, v5
	s_waitcnt vmcnt(12)
	v_mov_b32_e32 v34, v81
	v_mov_b32_e32 v35, v82
	v_mov_b32_e32 v81, v83
	v_mov_b32_e32 v82, v85
	v_mov_b32_e32 v83, v86
	v_mov_b32_e32 v85, v87
	v_pk_add_f32 v[80:81], v[34:35], v[80:81]
	v_pk_add_f32 v[82:83], v[82:83], v[84:85]
	v_pk_add_f32 v[80:81], v[80:81], v[80:81] op_sel:[0,1] op_sel_hi:[1,0]
	v_pk_add_f32 v[82:83], v[82:83], v[82:83] op_sel:[0,1] op_sel_hi:[1,0]
	v_add_f32_e32 v86, v88, v89
	v_add_f32_e32 v88, v90, v91
	v_mov_b32_e32 v87, v94
	v_mov_b32_e32 v89, v95
	v_mov_b32_e32 v81, v92
	v_mov_b32_e32 v83, v93
	v_pk_add_f32 v[84:85], v[86:87], v[88:89]
	v_pk_add_f32 v[80:81], v[80:81], v[82:83]
	s_nop 0
	v_pk_add_f32 v[80:81], v[80:81], v[84:85]
	s_nop 0
	v_add_f32_e32 v80, v80, v81
	v_fmamk_f32 v80, v80, 0x3a800000, v0
	v_mul_f32_e32 v81, 0x4b800000, v80
	v_cmp_gt_f32_e32 vcc, s1, v80
	s_nop 1
	v_cndmask_b32_e32 v80, v80, v81, vcc
	v_rsq_f32_e32 v80, v80
	s_nop 0
	v_mul_f32_e32 v81, 0x45800000, v80
	v_cndmask_b32_e32 v92, v80, v81, vcc
	v_pk_mul_f32 v[64:65], v[144:145], v[92:93] op_sel_hi:[1,0]
	v_pk_mul_f32 v[66:67], v[146:147], v[92:93] op_sel_hi:[1,0]
	v_pk_mul_f32 v[64:65], v[48:49], v[64:65]
	v_pk_mul_f32 v[66:67], v[50:51], v[66:67]
	global_store_dwordx4 v[38:39], v[64:67], off offset:-2048
	v_pk_mul_f32 v[68:69], v[148:149], v[92:93] op_sel_hi:[1,0]
	v_pk_mul_f32 v[70:71], v[150:151], v[92:93] op_sel_hi:[1,0]
	v_pk_mul_f32 v[68:69], v[52:53], v[68:69]
	v_pk_mul_f32 v[70:71], v[54:55], v[70:71]
	global_store_dwordx4 v[38:39], v[68:71], off offset:-1024
	v_pk_mul_f32 v[72:73], v[152:153], v[92:93] op_sel_hi:[1,0]
	v_pk_mul_f32 v[74:75], v[154:155], v[92:93] op_sel_hi:[1,0]
	v_pk_mul_f32 v[72:73], v[56:57], v[72:73]
	v_pk_mul_f32 v[74:75], v[58:59], v[74:75]
	global_store_dwordx4 v[38:39], v[72:75], off
	v_pk_mul_f32 v[76:77], v[156:157], v[92:93] op_sel_hi:[1,0]
	v_pk_mul_f32 v[78:79], v[158:159], v[92:93] op_sel_hi:[1,0]
	v_pk_mul_f32 v[76:77], v[60:61], v[76:77]
	v_pk_mul_f32 v[78:79], v[62:63], v[78:79]
	global_store_dwordx4 v[38:39], v[76:79], off offset:1024
	v_lshl_add_u64 v[38:39], v[38:39], 0, s[8:9]
	s_waitcnt vmcnt(12)
	v_mov_b32_e32 v34, v97
	v_mov_b32_e32 v35, v98
	v_mov_b32_e32 v97, v99
	v_mov_b32_e32 v98, v101
	v_mov_b32_e32 v99, v102
	v_mov_b32_e32 v101, v103
	v_pk_add_f32 v[96:97], v[34:35], v[96:97]
	v_pk_add_f32 v[98:99], v[98:99], v[100:101]
	v_pk_add_f32 v[96:97], v[96:97], v[96:97] op_sel:[0,1] op_sel_hi:[1,0]
	v_pk_add_f32 v[98:99], v[98:99], v[98:99] op_sel:[0,1] op_sel_hi:[1,0]
	v_add_f32_e32 v102, v104, v105
	v_add_f32_e32 v104, v106, v107
	v_mov_b32_e32 v103, v110
	v_mov_b32_e32 v105, v111
	v_mov_b32_e32 v97, v108
	v_mov_b32_e32 v99, v109
	v_pk_add_f32 v[100:101], v[102:103], v[104:105]
	v_pk_add_f32 v[96:97], v[96:97], v[98:99]
	s_nop 0
	v_pk_add_f32 v[96:97], v[96:97], v[100:101]
	s_nop 0
	v_add_f32_e32 v96, v96, v97
	v_fmamk_f32 v96, v96, 0x3a800000, v0
	v_mul_f32_e32 v97, 0x4b800000, v96
	v_cmp_gt_f32_e32 vcc, s1, v96
	s_nop 1
	v_cndmask_b32_e32 v96, v96, v97, vcc
	v_rsq_f32_e32 v96, v96
	s_nop 0
	v_mul_f32_e32 v97, 0x45800000, v96
	v_cndmask_b32_e32 v108, v96, v97, vcc
	v_pk_mul_f32 v[64:65], v[160:161], v[108:109] op_sel_hi:[1,0]
	v_pk_mul_f32 v[66:67], v[162:163], v[108:109] op_sel_hi:[1,0]
	v_pk_mul_f32 v[64:65], v[48:49], v[64:65]
	v_pk_mul_f32 v[66:67], v[50:51], v[66:67]
	global_store_dwordx4 v[38:39], v[64:67], off offset:-2048
	v_pk_mul_f32 v[68:69], v[164:165], v[108:109] op_sel_hi:[1,0]
	v_pk_mul_f32 v[70:71], v[166:167], v[108:109] op_sel_hi:[1,0]
	v_pk_mul_f32 v[68:69], v[52:53], v[68:69]
	v_pk_mul_f32 v[70:71], v[54:55], v[70:71]
	global_store_dwordx4 v[38:39], v[68:71], off offset:-1024
	v_pk_mul_f32 v[72:73], v[168:169], v[108:109] op_sel_hi:[1,0]
	v_pk_mul_f32 v[74:75], v[170:171], v[108:109] op_sel_hi:[1,0]
	v_pk_mul_f32 v[72:73], v[56:57], v[72:73]
	v_pk_mul_f32 v[74:75], v[58:59], v[74:75]
	global_store_dwordx4 v[38:39], v[72:75], off
	v_pk_mul_f32 v[76:77], v[172:173], v[108:109] op_sel_hi:[1,0]
	v_pk_mul_f32 v[78:79], v[174:175], v[108:109] op_sel_hi:[1,0]
	v_pk_mul_f32 v[76:77], v[60:61], v[76:77]
	v_pk_mul_f32 v[78:79], v[62:63], v[78:79]
	global_store_dwordx4 v[38:39], v[76:79], off offset:1024
	v_lshl_add_u64 v[38:39], v[38:39], 0, s[8:9]
	s_waitcnt vmcnt(12)
	v_mov_b32_e32 v34, v113
	v_mov_b32_e32 v35, v114
	v_mov_b32_e32 v113, v115
	v_mov_b32_e32 v114, v117
	v_mov_b32_e32 v115, v118
	v_mov_b32_e32 v117, v119
	v_pk_add_f32 v[112:113], v[34:35], v[112:113]
	v_pk_add_f32 v[114:115], v[114:115], v[116:117]
	v_pk_add_f32 v[112:113], v[112:113], v[112:113] op_sel:[0,1] op_sel_hi:[1,0]
	v_pk_add_f32 v[114:115], v[114:115], v[114:115] op_sel:[0,1] op_sel_hi:[1,0]
	v_add_f32_e32 v118, v120, v121
	v_add_f32_e32 v120, v122, v123
	v_mov_b32_e32 v119, v126
	v_mov_b32_e32 v121, v127
	v_mov_b32_e32 v113, v124
	v_mov_b32_e32 v115, v125
	v_pk_add_f32 v[116:117], v[118:119], v[120:121]
	v_pk_add_f32 v[112:113], v[112:113], v[114:115]
	s_nop 0
	v_pk_add_f32 v[112:113], v[112:113], v[116:117]
	s_nop 0
	v_add_f32_e32 v112, v112, v113
	v_fmamk_f32 v112, v112, 0x3a800000, v0
	v_mul_f32_e32 v113, 0x4b800000, v112
	v_cmp_gt_f32_e32 vcc, s1, v112
	s_nop 1
	v_cndmask_b32_e32 v112, v112, v113, vcc
	v_rsq_f32_e32 v112, v112
	s_nop 0
	v_mul_f32_e32 v113, 0x45800000, v112
	v_cndmask_b32_e32 v124, v112, v113, vcc
	v_pk_mul_f32 v[64:65], v[176:177], v[124:125] op_sel_hi:[1,0]
	v_pk_mul_f32 v[66:67], v[178:179], v[124:125] op_sel_hi:[1,0]
	v_pk_mul_f32 v[64:65], v[48:49], v[64:65]
	v_pk_mul_f32 v[66:67], v[50:51], v[66:67]
	global_store_dwordx4 v[38:39], v[64:67], off offset:-2048
	v_pk_mul_f32 v[68:69], v[180:181], v[124:125] op_sel_hi:[1,0]
	v_pk_mul_f32 v[70:71], v[182:183], v[124:125] op_sel_hi:[1,0]
	v_pk_mul_f32 v[68:69], v[52:53], v[68:69]
	v_pk_mul_f32 v[70:71], v[54:55], v[70:71]
	global_store_dwordx4 v[38:39], v[68:71], off offset:-1024
	v_pk_mul_f32 v[72:73], v[184:185], v[124:125] op_sel_hi:[1,0]
	v_pk_mul_f32 v[74:75], v[186:187], v[124:125] op_sel_hi:[1,0]
	v_pk_mul_f32 v[72:73], v[56:57], v[72:73]
	v_pk_mul_f32 v[74:75], v[58:59], v[74:75]
	global_store_dwordx4 v[38:39], v[72:75], off
	v_pk_mul_f32 v[76:77], v[188:189], v[124:125] op_sel_hi:[1,0]
	v_pk_mul_f32 v[78:79], v[190:191], v[124:125] op_sel_hi:[1,0]
	v_pk_mul_f32 v[76:77], v[60:61], v[76:77]
	v_pk_mul_f32 v[78:79], v[62:63], v[78:79]
	global_store_dwordx4 v[38:39], v[76:79], off offset:1024
	v_lshl_add_u64 v[38:39], v[38:39], 0, s[8:9]
	s_waitcnt vmcnt(12)
	v_mov_b32_e32 v34, v129
	v_mov_b32_e32 v35, v130
	v_mov_b32_e32 v129, v131
	v_mov_b32_e32 v130, v133
	v_mov_b32_e32 v131, v134
	v_mov_b32_e32 v133, v135
	v_pk_add_f32 v[128:129], v[34:35], v[128:129]
	v_pk_add_f32 v[130:131], v[130:131], v[132:133]
	v_pk_add_f32 v[128:129], v[128:129], v[128:129] op_sel:[0,1] op_sel_hi:[1,0]
	v_pk_add_f32 v[130:131], v[130:131], v[130:131] op_sel:[0,1] op_sel_hi:[1,0]
	v_add_f32_e32 v134, v136, v137
	v_add_f32_e32 v136, v138, v139
	v_mov_b32_e32 v135, v142
	v_mov_b32_e32 v137, v143
	v_mov_b32_e32 v129, v140
	v_mov_b32_e32 v131, v141
	v_pk_add_f32 v[132:133], v[134:135], v[136:137]
	v_pk_add_f32 v[128:129], v[128:129], v[130:131]
	s_nop 0
	v_pk_add_f32 v[128:129], v[128:129], v[132:133]
	s_nop 0
	v_add_f32_e32 v128, v128, v129
	v_fmamk_f32 v128, v128, 0x3a800000, v0
	v_mul_f32_e32 v129, 0x4b800000, v128
	v_cmp_gt_f32_e32 vcc, s1, v128
	s_nop 1
	v_cndmask_b32_e32 v128, v128, v129, vcc
	v_rsq_f32_e32 v128, v128
	s_nop 0
	v_mul_f32_e32 v129, 0x45800000, v128
	v_cndmask_b32_e32 v140, v128, v129, vcc
	v_pk_mul_f32 v[64:65], v[192:193], v[140:141] op_sel_hi:[1,0]
	v_pk_mul_f32 v[66:67], v[194:195], v[140:141] op_sel_hi:[1,0]
	v_pk_mul_f32 v[64:65], v[48:49], v[64:65]
	v_pk_mul_f32 v[66:67], v[50:51], v[66:67]
	global_store_dwordx4 v[38:39], v[64:67], off offset:-2048
	v_pk_mul_f32 v[68:69], v[196:197], v[140:141] op_sel_hi:[1,0]
	v_pk_mul_f32 v[70:71], v[198:199], v[140:141] op_sel_hi:[1,0]
	v_pk_mul_f32 v[68:69], v[52:53], v[68:69]
	v_pk_mul_f32 v[70:71], v[54:55], v[70:71]
	global_store_dwordx4 v[38:39], v[68:71], off offset:-1024
	v_pk_mul_f32 v[72:73], v[200:201], v[140:141] op_sel_hi:[1,0]
	v_pk_mul_f32 v[74:75], v[202:203], v[140:141] op_sel_hi:[1,0]
	v_pk_mul_f32 v[72:73], v[56:57], v[72:73]
	v_pk_mul_f32 v[74:75], v[58:59], v[74:75]
	global_store_dwordx4 v[38:39], v[72:75], off
	v_pk_mul_f32 v[76:77], v[204:205], v[140:141] op_sel_hi:[1,0]
	v_pk_mul_f32 v[78:79], v[206:207], v[140:141] op_sel_hi:[1,0]
	v_pk_mul_f32 v[76:77], v[60:61], v[76:77]
	v_pk_mul_f32 v[78:79], v[62:63], v[78:79]
	global_store_dwordx4 v[38:39], v[76:79], off offset:1024
	s_add_i32 s11, s11, s16
	s_add_u32 s2, s2, s18
	s_addc_u32 s3, s3, s19
	v_lshl_add_u64 v[4:5], v[4:5], 0, s[20:21]
	s_cmpk_lt_i32 s11, 0x4000
	s_cbranch_scc1 .LBB0_3405
